# P4 main weight-prep items: second load pair of each half issued before the first pair's wait (two extra register buffers, zero-initialised for masked lanes)
# baseline (speedup 1.0000x reference)
.LBB0_136:
	s_or_b64 exec, exec, s[24:25]
	v_add_u32_e32 v34, 0x18c0, v49
	s_waitcnt vmcnt(1)
	ds_write2_b32 v34, v228, v229 offset1:1
	v_add_u32_e32 v0, 0x18c8, v49
	ds_write2_b32 v0, v230, v231 offset1:1
	v_add_u32_e32 v0, 0x1ce0, v49
	s_waitcnt vmcnt(0)
	ds_write2_b32 v0, v232, v233 offset1:1
	v_add_u32_e32 v0, 0x1ce8, v49
	ds_write2_b32 v0, v234, v235 offset1:1
	s_waitcnt lgkmcnt(0)
	ds_read_b32 v0, v47
	ds_read_b32 v1, v47 offset:132
	s_ashr_i32 s21, s20, 31
	v_lshl_add_u64 v[4:5], s[20:21], 1, v[28:29]
	s_waitcnt lgkmcnt(0)
	v_cvt_pk_bf16_f32 v0, v0, v1
	ds_read_b32 v1, v47 offset:264
	ds_read_b32 v2, v47 offset:396
	s_waitcnt lgkmcnt(0)
	v_cvt_pk_bf16_f32 v1, v1, v2
	ds_read_b32 v2, v47 offset:528
	ds_read_b32 v3, v47 offset:660
	s_waitcnt lgkmcnt(0)
	v_cvt_pk_bf16_f32 v2, v2, v3
	ds_read_b32 v3, v47 offset:792
	ds_read_b32 v6, v47 offset:924
	s_waitcnt lgkmcnt(0)
	v_cvt_pk_bf16_f32 v3, v3, v6
	v_add_u32_e32 v6, s18, v37
	v_ashrrev_i32_e32 v7, 31, v6
	v_lshlrev_b64 v[6:7], 11, v[6:7]
	v_lshl_add_u64 v[6:7], v[4:5], 0, v[6:7]
	global_store_dwordx4 v[6:7], v[0:3], off
	ds_read_b32 v0, v47 offset:32
	ds_read_b32 v1, v47 offset:164
	s_waitcnt lgkmcnt(0)
	v_cvt_pk_bf16_f32 v0, v0, v1
	ds_read_b32 v1, v47 offset:296
	ds_read_b32 v2, v47 offset:428
	s_waitcnt lgkmcnt(0)
	v_cvt_pk_bf16_f32 v1, v1, v2
	ds_read_b32 v2, v47 offset:560
	ds_read_b32 v3, v47 offset:692
	s_waitcnt lgkmcnt(0)
	v_cvt_pk_bf16_f32 v2, v2, v3
	ds_read_b32 v3, v47 offset:824
	ds_read_b32 v6, v47 offset:956
	s_waitcnt lgkmcnt(0)
	v_cvt_pk_bf16_f32 v3, v3, v6
	v_add_u32_e32 v6, s18, v40
	v_ashrrev_i32_e32 v7, 31, v6
	v_lshlrev_b64 v[6:7], 11, v[6:7]
	v_lshl_add_u64 v[6:7], v[4:5], 0, v[6:7]
	global_store_dwordx4 v[6:7], v[0:3], off
	ds_read_b32 v0, v47 offset:64
	ds_read_b32 v1, v47 offset:196
	s_waitcnt lgkmcnt(0)
	v_cvt_pk_bf16_f32 v0, v0, v1
	ds_read_b32 v1, v47 offset:328
	ds_read_b32 v2, v47 offset:460
	s_waitcnt lgkmcnt(0)
	v_cvt_pk_bf16_f32 v1, v1, v2
	ds_read_b32 v2, v47 offset:592
	ds_read_b32 v3, v47 offset:724
	s_waitcnt lgkmcnt(0)
	v_cvt_pk_bf16_f32 v2, v2, v3
	ds_read_b32 v3, v47 offset:856
	ds_read_b32 v6, v47 offset:988
	s_waitcnt lgkmcnt(0)
	v_cvt_pk_bf16_f32 v3, v3, v6
	v_add_u32_e32 v6, s18, v41
	v_ashrrev_i32_e32 v7, 31, v6
	v_lshlrev_b64 v[6:7], 11, v[6:7]
	v_lshl_add_u64 v[6:7], v[4:5], 0, v[6:7]
	global_store_dwordx4 v[6:7], v[0:3], off
	ds_read_b32 v0, v47 offset:96
	ds_read_b32 v1, v47 offset:228
	s_waitcnt lgkmcnt(0)
	v_cvt_pk_bf16_f32 v0, v0, v1
	ds_read_b32 v1, v47 offset:360
	ds_read_b32 v2, v47 offset:492
	s_waitcnt lgkmcnt(0)
	v_cvt_pk_bf16_f32 v1, v1, v2
	ds_read_b32 v2, v47 offset:624
	ds_read_b32 v3, v47 offset:756
	s_waitcnt lgkmcnt(0)
	v_cvt_pk_bf16_f32 v2, v2, v3
	ds_read_b32 v3, v47 offset:888
	ds_read_b32 v6, v47 offset:1020
	s_waitcnt lgkmcnt(0)
	v_cvt_pk_bf16_f32 v3, v3, v6
	v_add_u32_e32 v6, s18, v42
	v_ashrrev_i32_e32 v7, 31, v6
	v_lshlrev_b64 v[6:7], 11, v[6:7]
	v_lshl_add_u64 v[4:5], v[4:5], 0, v[6:7]
	global_store_dwordx4 v[4:5], v[0:3], off
	s_waitcnt lgkmcnt(0)

.LBB0_190:
	s_or_saveexec_b64 s[24:25], s[20:21]
	v_lshlrev_b32_e32 v136, 2, v8
	s_lshl_b32 s20, s45, 6
	v_lshl_add_u64 v[34:35], s[26:27], 0, v[136:137]
	v_mov_b32_e32 v4, 0
	v_mov_b32_e32 v5, 0
	v_mov_b32_e32 v6, 0
	v_mov_b32_e32 v7, 0
	s_waitcnt lgkmcnt(0)
	v_mov_b32_e32 v228, 0
	v_mov_b32_e32 v229, 0
	v_mov_b32_e32 v230, 0
	v_mov_b32_e32 v231, 0
	v_mov_b32_e32 v232, 0
	v_mov_b32_e32 v233, 0
	v_mov_b32_e32 v234, 0
	v_mov_b32_e32 v235, 0
	v_mov_b32_e32 v0, 0
	v_mov_b32_e32 v1, 0
	v_mov_b32_e32 v2, 0
	v_mov_b32_e32 v3, 0
	s_xor_b64 exec, exec, s[24:25]
	s_cbranch_execz .LBB0_192
	v_add_u32_e32 v0, s20, v37
	v_mad_i64_i32 v[0:1], s[26:27], s22, v0, 0
	v_lshl_add_u64 v[0:1], v[0:1], 2, v[34:35]
	v_add_u32_e32 v4, s20, v40
	global_load_dwordx4 v[0:3], v[0:1], off
	v_mad_i64_i32 v[4:5], s[26:27], s22, v4, 0
	v_lshl_add_u64 v[4:5], v[4:5], 2, v[34:35]
	global_load_dwordx4 v[4:7], v[4:5], off
	v_add_u32_e32 v228, s20, v41
	v_add_u32_e32 v232, s20, v42
	v_mad_i64_i32 v[228:229], s[26:27], s22, v228, 0
	v_mad_i64_i32 v[232:233], s[26:27], s22, v232, 0
	v_lshl_add_u64 v[228:229], v[228:229], 2, v[34:35]
	v_lshl_add_u64 v[232:233], v[232:233], 2, v[34:35]
	global_load_dwordx4 v[228:231], v[228:229], off
	s_nop 0
	global_load_dwordx4 v[232:235], v[232:233], off
	s_waitcnt vmcnt(2)
	ds_write2_b32 v49, v0, v1 offset1:1
	ds_write2_b32 v49, v2, v3 offset0:2 offset1:3
	ds_write2_b32 v50, v4, v5 offset1:1
	ds_write2_b32 v51, v6, v7 offset1:1
.LBB0_192:
	s_or_b64 exec, exec, s[24:25]
	v_add_u32_e32 v50, 0x840, v49
	s_waitcnt vmcnt(0)
	ds_write2_b32 v50, v228, v229 offset1:1
	v_add_u32_e32 v0, 0x848, v49
	ds_write2_b32 v0, v230, v231 offset1:1
	v_add_u32_e32 v0, 0xc60, v49
	ds_write2_b32 v0, v232, v233 offset1:1
	v_add_u32_e32 v0, 0xc68, v49
	v_add_u32_e32 v50, 0x1080, v49
	v_add_u32_e32 v51, 0x1088, v49
	v_add_u32_e32 v52, 0x14a0, v49
	v_add_u32_e32 v53, 0x14a8, v49
	ds_write2_b32 v0, v234, v235 offset1:1
	s_and_saveexec_b64 s[24:25], vcc
	s_xor_b64 s[24:25], exec, s[24:25]
	s_cbranch_execz .LBB0_194
	ds_write2_b32 v50, v137, v137 offset1:1
	ds_write2_b32 v51, v137, v137 offset1:1
	ds_write2_b32 v52, v137, v137 offset1:1
	ds_write2_b32 v53, v137, v137 offset1:1
.LBB0_194:
	s_or_saveexec_b64 s[24:25], s[24:25]
	v_mov_b32_e32 v4, 0
	v_mov_b32_e32 v5, 0
	v_mov_b32_e32 v6, 0
	v_mov_b32_e32 v7, 0
	v_mov_b32_e32 v228, 0
	v_mov_b32_e32 v229, 0
	v_mov_b32_e32 v230, 0
	v_mov_b32_e32 v231, 0
	v_mov_b32_e32 v232, 0
	v_mov_b32_e32 v233, 0
	v_mov_b32_e32 v234, 0
	v_mov_b32_e32 v235, 0
	v_mov_b32_e32 v0, 0
	v_mov_b32_e32 v1, 0
	v_mov_b32_e32 v2, 0
	v_mov_b32_e32 v3, 0
	s_xor_b64 exec, exec, s[24:25]
	s_cbranch_execz .LBB0_136
	v_add_u32_e32 v0, s20, v43
	v_mad_i64_i32 v[0:1], s[26:27], s22, v0, 0
	v_lshl_add_u64 v[0:1], v[0:1], 2, v[34:35]
	v_add_u32_e32 v4, s20, v44
	global_load_dwordx4 v[0:3], v[0:1], off
	v_mad_i64_i32 v[4:5], s[26:27], s22, v4, 0
	v_lshl_add_u64 v[4:5], v[4:5], 2, v[34:35]
	global_load_dwordx4 v[4:7], v[4:5], off
	v_add_u32_e32 v228, s20, v45
	v_add_u32_e32 v232, s20, v46
	v_mad_i64_i32 v[228:229], s[26:27], s22, v228, 0
	v_mad_i64_i32 v[232:233], s[22:23], s22, v232, 0
	v_lshl_add_u64 v[228:229], v[228:229], 2, v[34:35]
	v_lshl_add_u64 v[232:233], v[232:233], 2, v[34:35]
	global_load_dwordx4 v[228:231], v[228:229], off
	s_nop 0
	global_load_dwordx4 v[232:235], v[232:233], off
	s_waitcnt vmcnt(3)
	ds_write2_b32 v50, v0, v1 offset1:1
	ds_write2_b32 v51, v2, v3 offset1:1
	s_waitcnt vmcnt(2)
	ds_write2_b32 v52, v4, v5 offset1:1
	ds_write2_b32 v53, v6, v7 offset1:1
	s_branch .LBB0_136
